# v39 plus adjacent scalar row-sum add pairs merged into v_pk_add_f32 in the attention exp/PV section
# baseline (speedup 1.0000x reference)
; #define LAS __attribute__((address_space(3)))
; __device__ __forceinline__ void a2_exp_pack(f32x16& st0, f32x16& st1, float& lsum, bf16x8 (&pf)[4]) {
;     float ps = 0.f;
; #pragma unroll
;     for (int r = 0; r < 16; ++r) { st0[r] = __builtin_amdgcn_exp2f(st0[r]); st1[r] = __builtin_amdgcn_exp2f(st1[r]); ps += st0[r] + st1[r]; }
;     lsum += ps;
;     u32x4 w;
;     w.x = cvtpk2(st0[0], st0[1]); w.y = cvtpk2(st0[2], st0[3]); w.z = cvtpk2(st0[4], st0[5]); w.w = cvtpk2(st0[6], st0[7]); pf[0] = __builtin_bit_cast(bf16x8, w);
;     w.x = cvtpk2(st0[8], st0[9]); w.y = cvtpk2(st0[10], st0[11]); w.z = cvtpk2(st0[12], st0[13]); w.w = cvtpk2(st0[14], st0[15]); pf[1] = __builtin_bit_cast(bf16x8, w);
;     w.x = cvtpk2(st1[0], st1[1]); w.y = cvtpk2(st1[2], st1[3]); w.z = cvtpk2(st1[4], st1[5]); w.w = cvtpk2(st1[6], st1[7]); pf[2] = __builtin_bit_cast(bf16x8, w);
;     w.x = cvtpk2(st1[8], st1[9]); w.y = cvtpk2(st1[10], st1[11]); w.z = cvtpk2(st1[12], st1[13]); w.w = cvtpk2(st1[14], st1[15]); pf[3] = __builtin_bit_cast(bf16x8, w);
; }
; __device__ __forceinline__ void a2_pv(const LAS unsigned char* vb, const bf16x8 (&pf)[4], f32x16& ot0, f32x16& ot1) {
; #pragma unroll
;     for (int s = 0; s < 4; ++s) {
;         const s16x4 a00 = __builtin_bit_cast(s16x4, __builtin_amdgcn_ds_read_tr16_b64_v4i16((LAS s16x4*)(vb + (16 * s) * 64)));
;         const s16x4 a01 = __builtin_bit_cast(s16x4, __builtin_amdgcn_ds_read_tr16_b64_v4i16((LAS s16x4*)(vb + (16 * s + 8) * 64)));
;         const s16x4 a10 = __builtin_bit_cast(s16x4, __builtin_amdgcn_ds_read_tr16_b64_v4i16((LAS s16x4*)(vb + 8192 + (16 * s) * 64)));
;         const s16x4 a11 = __builtin_bit_cast(s16x4, __builtin_amdgcn_ds_read_tr16_b64_v4i16((LAS s16x4*)(vb + 8192 + (16 * s + 8) * 64)));
;         const bf16x8 va0 = (bf16x8){a00[0], a00[1], a00[2], a00[3], a01[0], a01[1], a01[2], a01[3]};
;         const bf16x8 va1 = (bf16x8){a10[0], a10[1], a10[2], a10[3], a11[0], a11[1], a11[2], a11[3]};
; __device__ __forceinline__ void attn2_unit(bf16_t* Z, const bf16_t* Hb, const float* rc, const float* rs, LAS unsigned char* lds, int b, int h, int qblk) {
;     ...
;             a2_exp_pack(sa0, sa1, lsum, pa);
;             a2_pv(vb, pa, ot0, ot1);
;             a2_exp_pack(sb0, sb1, lsum, pb);
;             a2_pv(vb + 64 * 64, pb, ot0, ot1);
.LBB0_832:
	v_add_u32_e32 v0, v2, v218
	v_exp_f32_e32 v199, v112
	v_exp_f32_e32 v7, v96
	v_exp_f32_e32 v113, v113
	v_exp_f32_e32 v9, v97
	v_exp_f32_e32 v201, v114
	v_exp_f32_e32 v3, v98
	v_exp_f32_e32 v115, v115
	v_exp_f32_e32 v5, v99
	v_exp_f32_e32 v203, v116
	v_exp_f32_e32 v15, v117
	v_exp_f32_e32 v13, v118
	v_exp_f32_e32 v11, v119
	s_waitcnt vmcnt(0)
	ds_read_b64_tr_b16 v[96:97], v0 offset:26624
	ds_read_b64_tr_b16 v[98:99], v0 offset:27136
	ds_read_b64_tr_b16 v[214:215], v0 offset:34816
	ds_read_b64_tr_b16 v[216:217], v0 offset:35328
	ds_read_b64_tr_b16 v[224:225], v0 offset:27648
	ds_read_b64_tr_b16 v[226:227], v0 offset:28160
	v_cvt_pk_bf16_f32 v210, v199, v113
	v_cvt_pk_bf16_f32 v211, v201, v115
	v_cvt_pk_bf16_f32 v212, v203, v15
	v_cvt_pk_bf16_f32 v213, v13, v11
	v_exp_f32_e32 v209, v120
	v_exp_f32_e32 v207, v121
	s_waitcnt lgkmcnt(4)
	v_mfma_f32_32x32x16_bf16 v[16:31], v[96:99], v[210:213], v[16:31]
	v_exp_f32_e32 v205, v122
	v_exp_f32_e32 v121, v123
	v_exp_f32_e32 v117, v124
	ds_read_b64_tr_b16 v[228:229], v0 offset:35840
	ds_read_b64_tr_b16 v[230:231], v0 offset:36352
	v_exp_f32_e32 v119, v125
	v_exp_f32_e32 v99, v126
	v_exp_f32_e32 v97, v127
	s_waitcnt lgkmcnt(4)
	v_mfma_f32_32x32x16_bf16 v[32:47], v[214:217], v[210:213], v[32:47]
	v_cvt_pk_bf16_f32 v232, v209, v207
	v_cvt_pk_bf16_f32 v233, v205, v121
	v_cvt_pk_bf16_f32 v234, v117, v119
	v_cvt_pk_bf16_f32 v235, v99, v97
	v_exp_f32_e32 v125, v100
	v_exp_f32_e32 v213, v101
	v_exp_f32_e32 v211, v102
	s_waitcnt lgkmcnt(2)
	v_mfma_f32_32x32x16_bf16 v[16:31], v[224:227], v[232:235], v[16:31]
	v_exp_f32_e32 v217, v103
	ds_read_b64_tr_b16 v[224:225], v0 offset:28672
	ds_read_b64_tr_b16 v[226:227], v0 offset:29184
	v_cvt_pk_bf16_f32 v100, v7, v9
	v_cvt_pk_bf16_f32 v101, v3, v5
	v_cvt_pk_bf16_f32 v102, v125, v213
	v_cvt_pk_bf16_f32 v103, v211, v217
	v_exp_f32_e32 v123, v104
	s_waitcnt lgkmcnt(2)
	v_mfma_f32_32x32x16_bf16 v[32:47], v[228:231], v[232:235], v[32:47]
	ds_read_b64_tr_b16 v[228:229], v0 offset:36864
	ds_read_b64_tr_b16 v[230:231], v0 offset:37376
	ds_read_b64_tr_b16 v[232:233], v0 offset:29696
	ds_read_b64_tr_b16 v[234:235], v0 offset:30208
	v_exp_f32_e32 v127, v105
	v_exp_f32_e32 v105, v106
	v_exp_f32_e32 v215, v107
	v_exp_f32_e32 v107, v108
	v_exp_f32_e32 v109, v109
	v_exp_f32_e32 v198, v64
	s_waitcnt lgkmcnt(4)
	v_mfma_f32_32x32x16_bf16 v[16:31], v[224:227], v[100:103], v[16:31]
	ds_read_b64_tr_b16 v[224:225], v0 offset:37888
	ds_read_b64_tr_b16 v[226:227], v0 offset:38400
	v_exp_f32_e32 v6, v80
	v_exp_f32_e32 v112, v65
	v_exp_f32_e32 v8, v81
	v_exp_f32_e32 v200, v66
	v_exp_f32_e32 v2, v82
	v_exp_f32_e32 v114, v67
	s_waitcnt lgkmcnt(4)
	v_mfma_f32_32x32x16_bf16 v[32:47], v[228:231], v[100:103], v[32:47]
	v_exp_f32_e32 v103, v110
	v_exp_f32_e32 v101, v111
	v_exp_f32_e32 v4, v83
	v_cvt_pk_bf16_f32 v228, v123, v127
	v_cvt_pk_bf16_f32 v229, v105, v215
	v_cvt_pk_bf16_f32 v230, v107, v109
	v_cvt_pk_bf16_f32 v231, v103, v101
	v_pk_add_f32 v[64:65], v[6:7], v[198:199]
	v_pk_add_f32 v[66:67], v[8:9], v[112:113]
	s_waitcnt lgkmcnt(2)
	v_mfma_f32_32x32x16_bf16 v[16:31], v[232:235], v[228:231], v[16:31]
	v_pk_add_f32 v[64:65], v[64:65], 0 op_sel_hi:[1,0]
	v_exp_f32_e32 v202, v68
	v_pk_add_f32 v[64:65], v[66:67], v[64:65]
	v_pk_add_f32 v[66:67], v[2:3], v[200:201]
	v_exp_f32_e32 v14, v69
	v_pk_add_f32 v[64:65], v[66:67], v[64:65]
	v_pk_add_f32 v[66:67], v[4:5], v[114:115]
	s_waitcnt lgkmcnt(0)
	v_mfma_f32_32x32x16_bf16 v[32:47], v[224:227], v[228:231], v[32:47]
	v_pk_add_f32 v[110:111], v[66:67], v[64:65]
	v_exp_f32_e32 v12, v70
	v_exp_f32_e32 v10, v71
	ds_read_b64_tr_b16 v[64:65], v0 offset:30720
	ds_read_b64_tr_b16 v[66:67], v0 offset:31232
	v_exp_f32_e32 v124, v84
	v_exp_f32_e32 v208, v72
	v_exp_f32_e32 v206, v73
	v_exp_f32_e32 v204, v74
	v_exp_f32_e32 v120, v75
	ds_read_b64_tr_b16 v[72:73], v0 offset:38912
	ds_read_b64_tr_b16 v[74:75], v0 offset:39424
	ds_read_b64_tr_b16 v[80:81], v0 offset:31744
	ds_read_b64_tr_b16 v[82:83], v0 offset:32256
	v_exp_f32_e32 v212, v85
	v_cvt_pk_bf16_f32 v68, v198, v112
	v_cvt_pk_bf16_f32 v69, v200, v114
	v_cvt_pk_bf16_f32 v70, v202, v14
	v_cvt_pk_bf16_f32 v71, v12, v10
	v_pk_add_f32 v[220:221], v[124:125], v[202:203]
	v_exp_f32_e32 v210, v86
	s_waitcnt lgkmcnt(4)
; __device__ __forceinline__ void attn2_unit(bf16_t* Z, const bf16_t* Hb, const float* rc, const float* rs, LAS unsigned char* lds, int b, int h, int qblk) {
;     ...
;             a2_exp_pack(sa0, sa1, lsum, pa);
;             a2_pv(vb, pa, ot0, ot1);
;             a2_exp_pack(sb0, sb1, lsum, pb);
;             a2_pv(vb + 64 * 64, pb, ot0, ot1);
;         } else if (2 * kp <= cw) {
;             f32x16 sa0, sa1; bf16x8 pa[4];
;             a2_qk(kb, qf, cneg, sa0, sa1);
;             const float mt = a2_max(sa0, sa1);
;             if (kp == 0 || __builtin_amdgcn_ballot_w64(mt > 8.f) != 0ull) {
;                 const float delta = (kp == 0) ? mt : fmaxf(mt, 0.f), alpha = (kp == 0) ? 0.f : __builtin_amdgcn_exp2f(-delta);
;                 mrun += delta; lsum *= alpha;
; #pragma unroll
;                 for (int r = 0; r < 16; ++r) { ot0[r] *= alpha; ot1[r] *= alpha; sa0[r] -= delta; sa1[r] -= delta; cneg[r] = -mrun; }
;             }
;             a2_exp_pack(sa0, sa1, lsum, pa);
;             a2_pv(vb, pa, ot0, ot1);
;         }
;         __syncthreads();
;     }
	v_mfma_f32_32x32x16_bf16 v[16:31], v[64:67], v[68:71], v[16:31]
	v_pk_add_f32 v[64:65], v[220:221], v[110:111]
	v_pk_add_f32 v[14:15], v[212:213], v[14:15]
	v_exp_f32_e32 v216, v87
	v_exp_f32_e32 v116, v76
	v_exp_f32_e32 v118, v77
	v_exp_f32_e32 v98, v78
	v_exp_f32_e32 v96, v79
	s_waitcnt lgkmcnt(2)
	v_mfma_f32_32x32x16_bf16 v[32:47], v[72:75], v[68:71], v[32:47]
	v_pk_add_f32 v[14:15], v[14:15], v[64:65]
	ds_read_b64_tr_b16 v[64:65], v0 offset:39936
	ds_read_b64_tr_b16 v[66:67], v0 offset:40448
	v_exp_f32_e32 v122, v88
	v_pk_add_f32 v[12:13], v[210:211], v[12:13]
	v_pk_add_f32 v[68:69], v[216:217], v[10:11]
	v_pk_add_f32 v[14:15], v[12:13], v[14:15]
	v_cvt_pk_bf16_f32 v10, v208, v206
	v_cvt_pk_bf16_f32 v11, v204, v120
	v_cvt_pk_bf16_f32 v12, v116, v118
	v_cvt_pk_bf16_f32 v13, v98, v96
	v_pk_add_f32 v[14:15], v[68:69], v[14:15]
	v_pk_add_f32 v[68:69], v[122:123], v[208:209]
	s_waitcnt lgkmcnt(2)
	v_mfma_f32_32x32x16_bf16 v[16:31], v[80:83], v[10:13], v[16:31]
	v_pk_add_f32 v[14:15], v[68:69], v[14:15]
	ds_read_b64_tr_b16 v[68:69], v0 offset:32768
	ds_read_b64_tr_b16 v[70:71], v0 offset:33280
	v_exp_f32_e32 v126, v89
	v_exp_f32_e32 v104, v90
	v_cvt_pk_bf16_f32 v7, v2, v4
	v_exp_f32_e32 v214, v91
	v_cvt_pk_bf16_f32 v6, v6, v8
	s_waitcnt lgkmcnt(2)
	v_mfma_f32_32x32x16_bf16 v[32:47], v[64:67], v[10:13], v[32:47]
	ds_read_b64_tr_b16 v[2:3], v0 offset:40960
	ds_read_b64_tr_b16 v[4:5], v0 offset:41472
	ds_read_b64_tr_b16 v[10:11], v0 offset:33792
	ds_read_b64_tr_b16 v[12:13], v0 offset:34304
	v_cvt_pk_bf16_f32 v8, v124, v212
	v_cvt_pk_bf16_f32 v9, v210, v216
	v_pk_add_f32 v[72:73], v[126:127], v[206:207]
	v_pk_add_f32 v[64:65], v[104:105], v[204:205]
	v_pk_add_f32 v[14:15], v[72:73], v[14:15]
	v_exp_f32_e32 v106, v92
	s_waitcnt lgkmcnt(4)
	v_mfma_f32_32x32x16_bf16 v[16:31], v[68:71], v[6:9], v[16:31]
	v_pk_add_f32 v[14:15], v[64:65], v[14:15]
	v_pk_add_f32 v[64:65], v[214:215], v[120:121]
	v_exp_f32_e32 v108, v93
	v_exp_f32_e32 v102, v94
	v_exp_f32_e32 v100, v95
	v_pk_add_f32 v[14:15], v[64:65], v[14:15]
	ds_read_b64_tr_b16 v[64:65], v0 offset:41984
	ds_read_b64_tr_b16 v[66:67], v0 offset:42496
	s_waitcnt lgkmcnt(4)
	v_mfma_f32_32x32x16_bf16 v[32:47], v[2:5], v[6:9], v[32:47]
	v_pk_add_f32 v[2:3], v[106:107], v[116:117]
	v_cvt_pk_bf16_f32 v4, v106, v108
	v_pk_add_f32 v[6:7], v[2:3], v[14:15]
	v_cvt_pk_bf16_f32 v2, v122, v126
	v_cvt_pk_bf16_f32 v3, v104, v214
	v_cvt_pk_bf16_f32 v5, v102, v100
	v_pk_add_f32 v[8:9], v[108:109], v[118:119]
	v_mov_b32_e32 v14, v55
	s_waitcnt lgkmcnt(2)
	v_mfma_f32_32x32x16_bf16 v[16:31], v[10:13], v[2:5], v[16:31]
	v_pk_add_f32 v[6:7], v[8:9], v[6:7]
	v_pk_add_f32 v[8:9], v[102:103], v[98:99]
	v_mov_b32_e32 v10, v59
	v_pk_add_f32 v[6:7], v[8:9], v[6:7]
	v_pk_add_f32 v[8:9], v[100:101], v[96:97]
	v_mov_b32_e32 v11, v58
	v_pk_add_f32 v[6:7], v[8:9], v[6:7]
	s_waitcnt lgkmcnt(0)
	v_mfma_f32_32x32x16_bf16 v[32:47], v[64:67], v[2:5], v[32:47]
	v_add_f32_e32 v0, v169, v7
	v_add_f32_e32 v0, v6, v0
	s_add_i32 s65, s65, 1
	s_add_i32 s69, s69, 2
	s_add_i32 s6, s43, s65
	v_lshl_add_u64 v[176:177], v[176:177], 0, v[174:175]
	v_lshl_add_u64 v[178:179], v[178:179], 0, s[20:21]
	v_lshl_add_u64 v[180:181], v[180:181], 0, s[20:21]
	v_lshl_add_u64 v[184:185], v[184:185], 0, v[182:183]
	v_lshl_add_u64 v[188:189], v[188:189], 0, v[186:187]
	s_cmp_lg_u32 s6, 1
	v_lshl_add_u64 v[196:197], v[196:197], 0, v[190:191]
	s_waitcnt vmcnt(0) lgkmcnt(0)
	s_barrier
	s_cbranch_scc0 .Lattn_exit_0
	v_mov_b32_e32 v169, v0
	s_bitcmp1_b32 s65, 0
	s_cselect_b32 s6, 0, 0xa800
	s_cmp_ge_u32 s65, s36
	s_cbranch_scc0 .LBB0_810
	s_branch .LBB0_813

; #define LAS __attribute__((address_space(3)))
; __device__ __forceinline__ void a2_exp_pack(f32x16& st0, f32x16& st1, float& lsum, bf16x8 (&pf)[4]) {
;     float ps = 0.f;
; #pragma unroll
;     for (int r = 0; r < 16; ++r) { st0[r] = __builtin_amdgcn_exp2f(st0[r]); st1[r] = __builtin_amdgcn_exp2f(st1[r]); ps += st0[r] + st1[r]; }
;     lsum += ps;
;     u32x4 w;
;     w.x = cvtpk2(st0[0], st0[1]); w.y = cvtpk2(st0[2], st0[3]); w.z = cvtpk2(st0[4], st0[5]); w.w = cvtpk2(st0[6], st0[7]); pf[0] = __builtin_bit_cast(bf16x8, w);
;     w.x = cvtpk2(st0[8], st0[9]); w.y = cvtpk2(st0[10], st0[11]); w.z = cvtpk2(st0[12], st0[13]); w.w = cvtpk2(st0[14], st0[15]); pf[1] = __builtin_bit_cast(bf16x8, w);
;     w.x = cvtpk2(st1[0], st1[1]); w.y = cvtpk2(st1[2], st1[3]); w.z = cvtpk2(st1[4], st1[5]); w.w = cvtpk2(st1[6], st1[7]); pf[2] = __builtin_bit_cast(bf16x8, w);
;     w.x = cvtpk2(st1[8], st1[9]); w.y = cvtpk2(st1[10], st1[11]); w.z = cvtpk2(st1[12], st1[13]); w.w = cvtpk2(st1[14], st1[15]); pf[3] = __builtin_bit_cast(bf16x8, w);
; }
; __device__ __forceinline__ void a2_pv(const LAS unsigned char* vb, const bf16x8 (&pf)[4], f32x16& ot0, f32x16& ot1) {
; #pragma unroll
;     for (int s = 0; s < 4; ++s) {
;         const s16x4 a00 = __builtin_bit_cast(s16x4, __builtin_amdgcn_ds_read_tr16_b64_v4i16((LAS s16x4*)(vb + (16 * s) * 64)));
;         const s16x4 a01 = __builtin_bit_cast(s16x4, __builtin_amdgcn_ds_read_tr16_b64_v4i16((LAS s16x4*)(vb + (16 * s + 8) * 64)));
;         const s16x4 a10 = __builtin_bit_cast(s16x4, __builtin_amdgcn_ds_read_tr16_b64_v4i16((LAS s16x4*)(vb + 8192 + (16 * s) * 64)));
;         const s16x4 a11 = __builtin_bit_cast(s16x4, __builtin_amdgcn_ds_read_tr16_b64_v4i16((LAS s16x4*)(vb + 8192 + (16 * s + 8) * 64)));
;         const bf16x8 va0 = (bf16x8){a00[0], a00[1], a00[2], a00[3], a01[0], a01[1], a01[2], a01[3]};
;         const bf16x8 va1 = (bf16x8){a10[0], a10[1], a10[2], a10[3], a11[0], a11[1], a11[2], a11[3]};
; __device__ __forceinline__ void attn2_unit(bf16_t* Z, const bf16_t* Hb, const float* rc, const float* rs, LAS unsigned char* lds, int b, int h, int qblk) {
;     ...
;             a2_exp_pack(sa0, sa1, lsum, pa);
;             a2_pv(vb, pa, ot0, ot1);
;             a2_exp_pack(sb0, sb1, lsum, pb);
;             a2_pv(vb + 64 * 64, pb, ot0, ot1);
.LBB0_878:
	v_add_u32_e32 v0, v2, v218
	v_exp_f32_e32 v197, v112
	v_exp_f32_e32 v7, v96
	v_exp_f32_e32 v113, v113
	v_exp_f32_e32 v9, v97
	v_exp_f32_e32 v199, v114
	v_exp_f32_e32 v3, v98
	v_exp_f32_e32 v115, v115
	v_exp_f32_e32 v5, v99
	v_exp_f32_e32 v201, v116
	v_exp_f32_e32 v15, v117
	v_exp_f32_e32 v13, v118
	v_exp_f32_e32 v11, v119
	s_waitcnt vmcnt(0)
	ds_read_b64_tr_b16 v[96:97], v0 offset:26624
	ds_read_b64_tr_b16 v[98:99], v0 offset:27136
	ds_read_b64_tr_b16 v[212:213], v0 offset:34816
	ds_read_b64_tr_b16 v[214:215], v0 offset:35328
	ds_read_b64_tr_b16 v[224:225], v0 offset:27648
	ds_read_b64_tr_b16 v[226:227], v0 offset:28160
	v_cvt_pk_bf16_f32 v208, v197, v113
	v_cvt_pk_bf16_f32 v209, v199, v115
	v_cvt_pk_bf16_f32 v210, v201, v15
	v_cvt_pk_bf16_f32 v211, v13, v11
	v_exp_f32_e32 v207, v120
	v_exp_f32_e32 v205, v121
	s_waitcnt lgkmcnt(4)
	v_mfma_f32_32x32x16_bf16 v[16:31], v[96:99], v[208:211], v[16:31]
	v_exp_f32_e32 v203, v122
	v_exp_f32_e32 v121, v123
	v_exp_f32_e32 v117, v124
	ds_read_b64_tr_b16 v[228:229], v0 offset:35840
	ds_read_b64_tr_b16 v[230:231], v0 offset:36352
	v_exp_f32_e32 v119, v125
	v_exp_f32_e32 v99, v126
	v_exp_f32_e32 v97, v127
	s_waitcnt lgkmcnt(4)
	v_mfma_f32_32x32x16_bf16 v[32:47], v[212:215], v[208:211], v[32:47]
	v_cvt_pk_bf16_f32 v232, v207, v205
	v_cvt_pk_bf16_f32 v233, v203, v121
	v_cvt_pk_bf16_f32 v234, v117, v119
	v_cvt_pk_bf16_f32 v235, v99, v97
	v_exp_f32_e32 v125, v100
	v_exp_f32_e32 v211, v101
	v_exp_f32_e32 v209, v102
	s_waitcnt lgkmcnt(2)
	v_mfma_f32_32x32x16_bf16 v[16:31], v[224:227], v[232:235], v[16:31]
	v_exp_f32_e32 v215, v103
	ds_read_b64_tr_b16 v[224:225], v0 offset:28672
	ds_read_b64_tr_b16 v[226:227], v0 offset:29184
	v_cvt_pk_bf16_f32 v100, v7, v9
	v_cvt_pk_bf16_f32 v101, v3, v5
	v_cvt_pk_bf16_f32 v102, v125, v211
	v_cvt_pk_bf16_f32 v103, v209, v215
	v_exp_f32_e32 v123, v104
	s_waitcnt lgkmcnt(2)
	v_mfma_f32_32x32x16_bf16 v[32:47], v[228:231], v[232:235], v[32:47]
	ds_read_b64_tr_b16 v[228:229], v0 offset:36864
	ds_read_b64_tr_b16 v[230:231], v0 offset:37376
	ds_read_b64_tr_b16 v[232:233], v0 offset:29696
	ds_read_b64_tr_b16 v[234:235], v0 offset:30208
	v_exp_f32_e32 v127, v105
	v_exp_f32_e32 v105, v106
	v_exp_f32_e32 v213, v107
	v_exp_f32_e32 v107, v108
	v_exp_f32_e32 v109, v109
	v_exp_f32_e32 v196, v64
	s_waitcnt lgkmcnt(4)
	v_mfma_f32_32x32x16_bf16 v[16:31], v[224:227], v[100:103], v[16:31]
	ds_read_b64_tr_b16 v[224:225], v0 offset:37888
	ds_read_b64_tr_b16 v[226:227], v0 offset:38400
	v_exp_f32_e32 v6, v80
	v_exp_f32_e32 v112, v65
	v_exp_f32_e32 v8, v81
	v_exp_f32_e32 v198, v66
	v_exp_f32_e32 v2, v82
	v_exp_f32_e32 v114, v67
	s_waitcnt lgkmcnt(4)
	v_mfma_f32_32x32x16_bf16 v[32:47], v[228:231], v[100:103], v[32:47]
	v_exp_f32_e32 v103, v110
	v_exp_f32_e32 v101, v111
	v_exp_f32_e32 v4, v83
	v_cvt_pk_bf16_f32 v228, v123, v127
	v_cvt_pk_bf16_f32 v229, v105, v213
	v_cvt_pk_bf16_f32 v230, v107, v109
	v_cvt_pk_bf16_f32 v231, v103, v101
	v_pk_add_f32 v[64:65], v[6:7], v[196:197]
	v_pk_add_f32 v[66:67], v[8:9], v[112:113]
	s_waitcnt lgkmcnt(2)
	v_mfma_f32_32x32x16_bf16 v[16:31], v[232:235], v[228:231], v[16:31]
	v_pk_add_f32 v[64:65], v[64:65], 0 op_sel_hi:[1,0]
	v_exp_f32_e32 v200, v68
	v_pk_add_f32 v[64:65], v[66:67], v[64:65]
	v_pk_add_f32 v[66:67], v[2:3], v[198:199]
	v_exp_f32_e32 v14, v69
	v_pk_add_f32 v[64:65], v[66:67], v[64:65]
	v_pk_add_f32 v[66:67], v[4:5], v[114:115]
	s_waitcnt lgkmcnt(0)
	v_mfma_f32_32x32x16_bf16 v[32:47], v[224:227], v[228:231], v[32:47]
	v_pk_add_f32 v[110:111], v[66:67], v[64:65]
	v_exp_f32_e32 v12, v70
	v_exp_f32_e32 v10, v71
	ds_read_b64_tr_b16 v[64:65], v0 offset:30720
	ds_read_b64_tr_b16 v[66:67], v0 offset:31232
	v_exp_f32_e32 v124, v84
	v_exp_f32_e32 v206, v72
	v_exp_f32_e32 v204, v73
	v_exp_f32_e32 v202, v74
	v_exp_f32_e32 v120, v75
	ds_read_b64_tr_b16 v[72:73], v0 offset:38912
	ds_read_b64_tr_b16 v[74:75], v0 offset:39424
	ds_read_b64_tr_b16 v[80:81], v0 offset:31744
	ds_read_b64_tr_b16 v[82:83], v0 offset:32256
	v_exp_f32_e32 v210, v85
	v_cvt_pk_bf16_f32 v68, v196, v112
	v_cvt_pk_bf16_f32 v69, v198, v114
	v_cvt_pk_bf16_f32 v70, v200, v14
	v_cvt_pk_bf16_f32 v71, v12, v10
	v_pk_add_f32 v[216:217], v[124:125], v[200:201]
	v_exp_f32_e32 v208, v86
	s_waitcnt lgkmcnt(4)
; __device__ __forceinline__ void attn2_unit(bf16_t* Z, const bf16_t* Hb, const float* rc, const float* rs, LAS unsigned char* lds, int b, int h, int qblk) {
;     ...
;             a2_exp_pack(sa0, sa1, lsum, pa);
;             a2_pv(vb, pa, ot0, ot1);
;             a2_exp_pack(sb0, sb1, lsum, pb);
;             a2_pv(vb + 64 * 64, pb, ot0, ot1);
;         } else if (2 * kp <= cw) {
;             f32x16 sa0, sa1; bf16x8 pa[4];
;             a2_qk(kb, qf, cneg, sa0, sa1);
;             const float mt = a2_max(sa0, sa1);
;             if (kp == 0 || __builtin_amdgcn_ballot_w64(mt > 8.f) != 0ull) {
;                 const float delta = (kp == 0) ? mt : fmaxf(mt, 0.f), alpha = (kp == 0) ? 0.f : __builtin_amdgcn_exp2f(-delta);
;                 mrun += delta; lsum *= alpha;
; #pragma unroll
;                 for (int r = 0; r < 16; ++r) { ot0[r] *= alpha; ot1[r] *= alpha; sa0[r] -= delta; sa1[r] -= delta; cneg[r] = -mrun; }
;             }
;             a2_exp_pack(sa0, sa1, lsum, pa);
;             a2_pv(vb, pa, ot0, ot1);
;         }
;         __syncthreads();
;     }
	v_mfma_f32_32x32x16_bf16 v[16:31], v[64:67], v[68:71], v[16:31]
	v_pk_add_f32 v[64:65], v[216:217], v[110:111]
	v_pk_add_f32 v[14:15], v[210:211], v[14:15]
	v_exp_f32_e32 v214, v87
	v_exp_f32_e32 v116, v76
	v_exp_f32_e32 v118, v77
	v_exp_f32_e32 v98, v78
	v_exp_f32_e32 v96, v79
	s_waitcnt lgkmcnt(2)
	v_mfma_f32_32x32x16_bf16 v[32:47], v[72:75], v[68:71], v[32:47]
	v_pk_add_f32 v[14:15], v[14:15], v[64:65]
	ds_read_b64_tr_b16 v[64:65], v0 offset:39936
	ds_read_b64_tr_b16 v[66:67], v0 offset:40448
	v_exp_f32_e32 v122, v88
	v_pk_add_f32 v[12:13], v[208:209], v[12:13]
	v_pk_add_f32 v[68:69], v[214:215], v[10:11]
	v_pk_add_f32 v[14:15], v[12:13], v[14:15]
	v_cvt_pk_bf16_f32 v10, v206, v204
	v_cvt_pk_bf16_f32 v11, v202, v120
	v_cvt_pk_bf16_f32 v12, v116, v118
	v_cvt_pk_bf16_f32 v13, v98, v96
	v_pk_add_f32 v[14:15], v[68:69], v[14:15]
	v_pk_add_f32 v[68:69], v[122:123], v[206:207]
	s_waitcnt lgkmcnt(2)
	v_mfma_f32_32x32x16_bf16 v[16:31], v[80:83], v[10:13], v[16:31]
	v_pk_add_f32 v[14:15], v[68:69], v[14:15]
	ds_read_b64_tr_b16 v[68:69], v0 offset:32768
	ds_read_b64_tr_b16 v[70:71], v0 offset:33280
	v_exp_f32_e32 v126, v89
	v_exp_f32_e32 v104, v90
	v_cvt_pk_bf16_f32 v7, v2, v4
	v_exp_f32_e32 v212, v91
	v_cvt_pk_bf16_f32 v6, v6, v8
	s_waitcnt lgkmcnt(2)
	v_mfma_f32_32x32x16_bf16 v[32:47], v[64:67], v[10:13], v[32:47]
	ds_read_b64_tr_b16 v[2:3], v0 offset:40960
	ds_read_b64_tr_b16 v[4:5], v0 offset:41472
	ds_read_b64_tr_b16 v[10:11], v0 offset:33792
	ds_read_b64_tr_b16 v[12:13], v0 offset:34304
	v_cvt_pk_bf16_f32 v8, v124, v210
	v_cvt_pk_bf16_f32 v9, v208, v214
	v_pk_add_f32 v[72:73], v[126:127], v[204:205]
	v_pk_add_f32 v[64:65], v[104:105], v[202:203]
	v_pk_add_f32 v[14:15], v[72:73], v[14:15]
	v_exp_f32_e32 v106, v92
	s_waitcnt lgkmcnt(4)
	v_mfma_f32_32x32x16_bf16 v[16:31], v[68:71], v[6:9], v[16:31]
	v_pk_add_f32 v[14:15], v[64:65], v[14:15]
	v_pk_add_f32 v[64:65], v[212:213], v[120:121]
	v_exp_f32_e32 v108, v93
	v_exp_f32_e32 v102, v94
	v_exp_f32_e32 v100, v95
	v_pk_add_f32 v[14:15], v[64:65], v[14:15]
	ds_read_b64_tr_b16 v[64:65], v0 offset:41984
	ds_read_b64_tr_b16 v[66:67], v0 offset:42496
	s_waitcnt lgkmcnt(4)
	v_mfma_f32_32x32x16_bf16 v[32:47], v[2:5], v[6:9], v[32:47]
	v_pk_add_f32 v[2:3], v[106:107], v[116:117]
	v_cvt_pk_bf16_f32 v4, v106, v108
	v_pk_add_f32 v[6:7], v[2:3], v[14:15]
	v_cvt_pk_bf16_f32 v2, v122, v126
	v_cvt_pk_bf16_f32 v3, v104, v212
	v_cvt_pk_bf16_f32 v5, v102, v100
	v_pk_add_f32 v[8:9], v[108:109], v[118:119]
	v_mov_b32_e32 v14, v55
	s_waitcnt lgkmcnt(2)
	v_mfma_f32_32x32x16_bf16 v[16:31], v[10:13], v[2:5], v[16:31]
	v_pk_add_f32 v[6:7], v[8:9], v[6:7]
	v_pk_add_f32 v[8:9], v[102:103], v[98:99]
	v_mov_b32_e32 v10, v59
	v_pk_add_f32 v[6:7], v[8:9], v[6:7]
	v_pk_add_f32 v[8:9], v[100:101], v[96:97]
	v_mov_b32_e32 v11, v58
	v_pk_add_f32 v[6:7], v[8:9], v[6:7]
	s_waitcnt lgkmcnt(0)
	v_mfma_f32_32x32x16_bf16 v[32:47], v[64:67], v[2:5], v[32:47]
	v_add_f32_e32 v0, v169, v7
	v_add_f32_e32 v0, v6, v0
	s_add_i32 s35, s35, 1
	s_add_i32 s56, s56, 2
	s_add_i32 s6, s46, s35
	v_lshl_add_u64 v[174:175], v[174:175], 0, v[170:171]
	v_lshl_add_u64 v[176:177], v[176:177], 0, s[20:21]
	v_lshl_add_u64 v[178:179], v[178:179], 0, s[20:21]
	v_lshl_add_u64 v[182:183], v[182:183], 0, v[180:181]
	v_lshl_add_u64 v[186:187], v[186:187], 0, v[184:185]
	s_cmp_lg_u32 s6, 1
	v_lshl_add_u64 v[190:191], v[190:191], 0, v[188:189]
	s_waitcnt vmcnt(0) lgkmcnt(0)
	s_barrier
	s_cbranch_scc0 .Lattn_exit_1
	v_mov_b32_e32 v169, v0
	s_bitcmp1_b32 s35, 0
	s_cselect_b32 s6, 0, 0xa800
	s_cmp_ge_u32 s35, s42
	s_cbranch_scc0 .LBB0_856
	s_branch .LBB0_859

; #define LAS __attribute__((address_space(3)))
; __device__ __forceinline__ void a2_exp_pack(f32x16& st0, f32x16& st1, float& lsum, bf16x8 (&pf)[4]) {
;     float ps = 0.f;
; #pragma unroll
;     for (int r = 0; r < 16; ++r) { st0[r] = __builtin_amdgcn_exp2f(st0[r]); st1[r] = __builtin_amdgcn_exp2f(st1[r]); ps += st0[r] + st1[r]; }
;     lsum += ps;
;     u32x4 w;
;     w.x = cvtpk2(st0[0], st0[1]); w.y = cvtpk2(st0[2], st0[3]); w.z = cvtpk2(st0[4], st0[5]); w.w = cvtpk2(st0[6], st0[7]); pf[0] = __builtin_bit_cast(bf16x8, w);
;     w.x = cvtpk2(st0[8], st0[9]); w.y = cvtpk2(st0[10], st0[11]); w.z = cvtpk2(st0[12], st0[13]); w.w = cvtpk2(st0[14], st0[15]); pf[1] = __builtin_bit_cast(bf16x8, w);
;     w.x = cvtpk2(st1[0], st1[1]); w.y = cvtpk2(st1[2], st1[3]); w.z = cvtpk2(st1[4], st1[5]); w.w = cvtpk2(st1[6], st1[7]); pf[2] = __builtin_bit_cast(bf16x8, w);
;     w.x = cvtpk2(st1[8], st1[9]); w.y = cvtpk2(st1[10], st1[11]); w.z = cvtpk2(st1[12], st1[13]); w.w = cvtpk2(st1[14], st1[15]); pf[3] = __builtin_bit_cast(bf16x8, w);
; }
; __device__ __forceinline__ void a2_pv(const LAS unsigned char* vb, const bf16x8 (&pf)[4], f32x16& ot0, f32x16& ot1) {
; #pragma unroll
;     for (int s = 0; s < 4; ++s) {
;         const s16x4 a00 = __builtin_bit_cast(s16x4, __builtin_amdgcn_ds_read_tr16_b64_v4i16((LAS s16x4*)(vb + (16 * s) * 64)));
;         const s16x4 a01 = __builtin_bit_cast(s16x4, __builtin_amdgcn_ds_read_tr16_b64_v4i16((LAS s16x4*)(vb + (16 * s + 8) * 64)));
;         const s16x4 a10 = __builtin_bit_cast(s16x4, __builtin_amdgcn_ds_read_tr16_b64_v4i16((LAS s16x4*)(vb + 8192 + (16 * s) * 64)));
;         const s16x4 a11 = __builtin_bit_cast(s16x4, __builtin_amdgcn_ds_read_tr16_b64_v4i16((LAS s16x4*)(vb + 8192 + (16 * s + 8) * 64)));
;         const bf16x8 va0 = (bf16x8){a00[0], a00[1], a00[2], a00[3], a01[0], a01[1], a01[2], a01[3]};
;         const bf16x8 va1 = (bf16x8){a10[0], a10[1], a10[2], a10[3], a11[0], a11[1], a11[2], a11[3]};
; __device__ __forceinline__ void attn2_unit(bf16_t* Z, const bf16_t* Hb, const float* rc, const float* rs, LAS unsigned char* lds, int b, int h, int qblk) {
;     ...
;             a2_exp_pack(sa0, sa1, lsum, pa);
;             a2_pv(vb, pa, ot0, ot1);
;             a2_exp_pack(sb0, sb1, lsum, pb);
;             a2_pv(vb + 64 * 64, pb, ot0, ot1);
.LBB0_2243:
	v_add_u32_e32 v0, v2, v218
	v_exp_f32_e32 v199, v112
	v_exp_f32_e32 v7, v96
	v_exp_f32_e32 v113, v113
	v_exp_f32_e32 v9, v97
	v_exp_f32_e32 v201, v114
	v_exp_f32_e32 v3, v98
	v_exp_f32_e32 v115, v115
	v_exp_f32_e32 v5, v99
	v_exp_f32_e32 v203, v116
	v_exp_f32_e32 v15, v117
	v_exp_f32_e32 v13, v118
	v_exp_f32_e32 v11, v119
	s_waitcnt vmcnt(0)
	ds_read_b64_tr_b16 v[96:97], v0 offset:26624
	ds_read_b64_tr_b16 v[98:99], v0 offset:27136
	ds_read_b64_tr_b16 v[214:215], v0 offset:34816
	ds_read_b64_tr_b16 v[216:217], v0 offset:35328
	ds_read_b64_tr_b16 v[220:221], v0 offset:27648
	ds_read_b64_tr_b16 v[222:223], v0 offset:28160
	v_cvt_pk_bf16_f32 v210, v199, v113
	v_cvt_pk_bf16_f32 v211, v201, v115
	v_cvt_pk_bf16_f32 v212, v203, v15
	v_cvt_pk_bf16_f32 v213, v13, v11
	v_exp_f32_e32 v209, v120
	v_exp_f32_e32 v207, v121
	s_waitcnt lgkmcnt(4)
	v_mfma_f32_32x32x16_bf16 v[16:31], v[96:99], v[210:213], v[16:31]
	v_exp_f32_e32 v205, v122
	v_exp_f32_e32 v121, v123
	v_exp_f32_e32 v117, v124
	ds_read_b64_tr_b16 v[224:225], v0 offset:35840
	ds_read_b64_tr_b16 v[226:227], v0 offset:36352
	v_exp_f32_e32 v119, v125
	v_exp_f32_e32 v99, v126
	v_exp_f32_e32 v97, v127
	s_waitcnt lgkmcnt(4)
	v_mfma_f32_32x32x16_bf16 v[32:47], v[214:217], v[210:213], v[32:47]
	v_cvt_pk_bf16_f32 v228, v209, v207
	v_cvt_pk_bf16_f32 v229, v205, v121
	v_cvt_pk_bf16_f32 v230, v117, v119
	v_cvt_pk_bf16_f32 v231, v99, v97
	v_exp_f32_e32 v125, v100
	v_exp_f32_e32 v213, v101
	v_exp_f32_e32 v211, v102
	s_waitcnt lgkmcnt(2)
	v_mfma_f32_32x32x16_bf16 v[16:31], v[220:223], v[228:231], v[16:31]
	v_exp_f32_e32 v217, v103
	ds_read_b64_tr_b16 v[220:221], v0 offset:28672
	ds_read_b64_tr_b16 v[222:223], v0 offset:29184
	v_cvt_pk_bf16_f32 v100, v7, v9
	v_cvt_pk_bf16_f32 v101, v3, v5
	v_cvt_pk_bf16_f32 v102, v125, v213
	v_cvt_pk_bf16_f32 v103, v211, v217
	v_exp_f32_e32 v123, v104
	s_waitcnt lgkmcnt(2)
	v_mfma_f32_32x32x16_bf16 v[32:47], v[224:227], v[228:231], v[32:47]
	ds_read_b64_tr_b16 v[224:225], v0 offset:36864
	ds_read_b64_tr_b16 v[226:227], v0 offset:37376
	ds_read_b64_tr_b16 v[228:229], v0 offset:29696
	ds_read_b64_tr_b16 v[230:231], v0 offset:30208
	v_exp_f32_e32 v127, v105
	v_exp_f32_e32 v105, v106
	v_exp_f32_e32 v215, v107
	v_exp_f32_e32 v107, v108
	v_exp_f32_e32 v109, v109
	v_exp_f32_e32 v198, v64
	s_waitcnt lgkmcnt(4)
	v_mfma_f32_32x32x16_bf16 v[16:31], v[220:223], v[100:103], v[16:31]
	ds_read_b64_tr_b16 v[220:221], v0 offset:37888
	ds_read_b64_tr_b16 v[222:223], v0 offset:38400
	v_exp_f32_e32 v6, v80
	v_exp_f32_e32 v112, v65
	v_exp_f32_e32 v8, v81
	v_exp_f32_e32 v200, v66
	v_exp_f32_e32 v2, v82
	v_exp_f32_e32 v114, v67
	s_waitcnt lgkmcnt(4)
	v_mfma_f32_32x32x16_bf16 v[32:47], v[224:227], v[100:103], v[32:47]
	v_exp_f32_e32 v103, v110
	v_exp_f32_e32 v101, v111
	v_exp_f32_e32 v4, v83
	v_cvt_pk_bf16_f32 v224, v123, v127
	v_cvt_pk_bf16_f32 v225, v105, v215
	v_cvt_pk_bf16_f32 v226, v107, v109
	v_cvt_pk_bf16_f32 v227, v103, v101
	v_pk_add_f32 v[64:65], v[6:7], v[198:199]
	v_pk_add_f32 v[66:67], v[8:9], v[112:113]
	s_waitcnt lgkmcnt(2)
	v_mfma_f32_32x32x16_bf16 v[16:31], v[228:231], v[224:227], v[16:31]
	v_pk_add_f32 v[64:65], v[64:65], 0 op_sel_hi:[1,0]
	v_exp_f32_e32 v202, v68
	v_pk_add_f32 v[64:65], v[66:67], v[64:65]
	v_pk_add_f32 v[66:67], v[2:3], v[200:201]
	v_exp_f32_e32 v14, v69
	v_pk_add_f32 v[64:65], v[66:67], v[64:65]
	v_pk_add_f32 v[66:67], v[4:5], v[114:115]
	s_waitcnt lgkmcnt(0)
	v_mfma_f32_32x32x16_bf16 v[32:47], v[220:223], v[224:227], v[32:47]
	v_pk_add_f32 v[110:111], v[66:67], v[64:65]
	v_exp_f32_e32 v12, v70
	v_exp_f32_e32 v10, v71
	ds_read_b64_tr_b16 v[64:65], v0 offset:30720
	ds_read_b64_tr_b16 v[66:67], v0 offset:31232
	v_exp_f32_e32 v124, v84
	v_exp_f32_e32 v208, v72
	v_exp_f32_e32 v206, v73
	v_exp_f32_e32 v204, v74
	v_exp_f32_e32 v120, v75
	ds_read_b64_tr_b16 v[72:73], v0 offset:38912
	ds_read_b64_tr_b16 v[74:75], v0 offset:39424
	ds_read_b64_tr_b16 v[80:81], v0 offset:31744
	ds_read_b64_tr_b16 v[82:83], v0 offset:32256
	v_exp_f32_e32 v212, v85
	v_cvt_pk_bf16_f32 v68, v198, v112
	v_cvt_pk_bf16_f32 v69, v200, v114
	v_cvt_pk_bf16_f32 v70, v202, v14
	v_cvt_pk_bf16_f32 v71, v12, v10
	v_pk_add_f32 v[220:221], v[124:125], v[202:203]
	v_exp_f32_e32 v210, v86
	s_waitcnt lgkmcnt(4)
; __device__ __forceinline__ void attn2_unit(bf16_t* Z, const bf16_t* Hb, const float* rc, const float* rs, LAS unsigned char* lds, int b, int h, int qblk) {
;     ...
;             a2_exp_pack(sa0, sa1, lsum, pa);
;             a2_pv(vb, pa, ot0, ot1);
;             a2_exp_pack(sb0, sb1, lsum, pb);
;             a2_pv(vb + 64 * 64, pb, ot0, ot1);
;         } else if (2 * kp <= cw) {
;             f32x16 sa0, sa1; bf16x8 pa[4];
;             a2_qk(kb, qf, cneg, sa0, sa1);
;             const float mt = a2_max(sa0, sa1);
;             if (kp == 0 || __builtin_amdgcn_ballot_w64(mt > 8.f) != 0ull) {
;                 const float delta = (kp == 0) ? mt : fmaxf(mt, 0.f), alpha = (kp == 0) ? 0.f : __builtin_amdgcn_exp2f(-delta);
;                 mrun += delta; lsum *= alpha;
; #pragma unroll
;                 for (int r = 0; r < 16; ++r) { ot0[r] *= alpha; ot1[r] *= alpha; sa0[r] -= delta; sa1[r] -= delta; cneg[r] = -mrun; }
;             }
;             a2_exp_pack(sa0, sa1, lsum, pa);
;             a2_pv(vb, pa, ot0, ot1);
;         }
;         __syncthreads();
;     }
	v_mfma_f32_32x32x16_bf16 v[16:31], v[64:67], v[68:71], v[16:31]
	v_pk_add_f32 v[64:65], v[220:221], v[110:111]
	v_pk_add_f32 v[14:15], v[212:213], v[14:15]
	v_exp_f32_e32 v216, v87
	v_exp_f32_e32 v116, v76
	v_exp_f32_e32 v118, v77
	v_exp_f32_e32 v98, v78
	v_exp_f32_e32 v96, v79
	s_waitcnt lgkmcnt(2)
	v_mfma_f32_32x32x16_bf16 v[32:47], v[72:75], v[68:71], v[32:47]
	v_pk_add_f32 v[14:15], v[14:15], v[64:65]
	ds_read_b64_tr_b16 v[64:65], v0 offset:39936
	ds_read_b64_tr_b16 v[66:67], v0 offset:40448
	v_exp_f32_e32 v122, v88
	v_pk_add_f32 v[12:13], v[210:211], v[12:13]
	v_pk_add_f32 v[68:69], v[216:217], v[10:11]
	v_pk_add_f32 v[14:15], v[12:13], v[14:15]
	v_cvt_pk_bf16_f32 v10, v208, v206
	v_cvt_pk_bf16_f32 v11, v204, v120
	v_cvt_pk_bf16_f32 v12, v116, v118
	v_cvt_pk_bf16_f32 v13, v98, v96
	v_pk_add_f32 v[14:15], v[68:69], v[14:15]
	v_pk_add_f32 v[68:69], v[122:123], v[208:209]
	s_waitcnt lgkmcnt(2)
	v_mfma_f32_32x32x16_bf16 v[16:31], v[80:83], v[10:13], v[16:31]
	v_pk_add_f32 v[14:15], v[68:69], v[14:15]
	ds_read_b64_tr_b16 v[68:69], v0 offset:32768
	ds_read_b64_tr_b16 v[70:71], v0 offset:33280
	v_exp_f32_e32 v126, v89
	v_exp_f32_e32 v104, v90
	v_cvt_pk_bf16_f32 v7, v2, v4
	v_exp_f32_e32 v214, v91
	v_cvt_pk_bf16_f32 v6, v6, v8
	s_waitcnt lgkmcnt(2)
	v_mfma_f32_32x32x16_bf16 v[32:47], v[64:67], v[10:13], v[32:47]
	ds_read_b64_tr_b16 v[2:3], v0 offset:40960
	ds_read_b64_tr_b16 v[4:5], v0 offset:41472
	ds_read_b64_tr_b16 v[10:11], v0 offset:33792
	ds_read_b64_tr_b16 v[12:13], v0 offset:34304
	v_cvt_pk_bf16_f32 v8, v124, v212
	v_cvt_pk_bf16_f32 v9, v210, v216
	v_pk_add_f32 v[72:73], v[126:127], v[206:207]
	v_pk_add_f32 v[64:65], v[104:105], v[204:205]
	v_pk_add_f32 v[14:15], v[72:73], v[14:15]
	v_exp_f32_e32 v106, v92
	s_waitcnt lgkmcnt(4)
	v_mfma_f32_32x32x16_bf16 v[16:31], v[68:71], v[6:9], v[16:31]
	v_pk_add_f32 v[14:15], v[64:65], v[14:15]
	v_pk_add_f32 v[64:65], v[214:215], v[120:121]
	v_exp_f32_e32 v108, v93
	v_exp_f32_e32 v102, v94
	v_exp_f32_e32 v100, v95
	v_pk_add_f32 v[14:15], v[64:65], v[14:15]
	ds_read_b64_tr_b16 v[64:65], v0 offset:41984
	ds_read_b64_tr_b16 v[66:67], v0 offset:42496
	s_waitcnt lgkmcnt(4)
	v_mfma_f32_32x32x16_bf16 v[32:47], v[2:5], v[6:9], v[32:47]
	v_pk_add_f32 v[2:3], v[106:107], v[116:117]
	v_cvt_pk_bf16_f32 v4, v106, v108
	v_pk_add_f32 v[6:7], v[2:3], v[14:15]
	v_cvt_pk_bf16_f32 v2, v122, v126
	v_cvt_pk_bf16_f32 v3, v104, v214
	v_cvt_pk_bf16_f32 v5, v102, v100
	v_pk_add_f32 v[8:9], v[108:109], v[118:119]
	v_mov_b32_e32 v14, v55
	s_waitcnt lgkmcnt(2)
	v_mfma_f32_32x32x16_bf16 v[16:31], v[10:13], v[2:5], v[16:31]
	v_pk_add_f32 v[6:7], v[8:9], v[6:7]
	v_pk_add_f32 v[8:9], v[102:103], v[98:99]
	v_mov_b32_e32 v10, v59
	v_pk_add_f32 v[6:7], v[8:9], v[6:7]
	v_pk_add_f32 v[8:9], v[100:101], v[96:97]
	v_mov_b32_e32 v11, v58
	v_pk_add_f32 v[6:7], v[8:9], v[6:7]
	s_waitcnt lgkmcnt(0)
	v_mfma_f32_32x32x16_bf16 v[32:47], v[64:67], v[2:5], v[32:47]
	v_add_f32_e32 v0, v169, v7
	v_add_f32_e32 v0, v6, v0
	s_add_i32 s47, s47, 1
	s_add_i32 s48, s48, 2
	s_add_i32 s6, s37, s47
	v_lshl_add_u64 v[176:177], v[176:177], 0, v[174:175]
	v_lshl_add_u64 v[178:179], v[178:179], 0, s[18:19]
	v_lshl_add_u64 v[180:181], v[180:181], 0, s[18:19]
	v_lshl_add_u64 v[184:185], v[184:185], 0, v[182:183]
	v_lshl_add_u64 v[188:189], v[188:189], 0, v[186:187]
	s_cmp_lg_u32 s6, 1
	v_lshl_add_u64 v[194:195], v[194:195], 0, v[190:191]
	s_waitcnt vmcnt(0) lgkmcnt(0)
	s_barrier
	s_cbranch_scc0 .Lattn_exit_2
	v_mov_b32_e32 v169, v0
	s_bitcmp1_b32 s47, 0
	s_cselect_b32 s6, 0, 0xa800
	s_cmp_ge_u32 s47, s34
	s_cbranch_scc0 .LBB0_2221
	s_branch .LBB0_2224

; #define LAS __attribute__((address_space(3)))
; __device__ __forceinline__ void a2_exp_pack(f32x16& st0, f32x16& st1, float& lsum, bf16x8 (&pf)[4]) {
;     float ps = 0.f;
; #pragma unroll
;     for (int r = 0; r < 16; ++r) { st0[r] = __builtin_amdgcn_exp2f(st0[r]); st1[r] = __builtin_amdgcn_exp2f(st1[r]); ps += st0[r] + st1[r]; }
;     lsum += ps;
;     u32x4 w;
;     w.x = cvtpk2(st0[0], st0[1]); w.y = cvtpk2(st0[2], st0[3]); w.z = cvtpk2(st0[4], st0[5]); w.w = cvtpk2(st0[6], st0[7]); pf[0] = __builtin_bit_cast(bf16x8, w);
;     w.x = cvtpk2(st0[8], st0[9]); w.y = cvtpk2(st0[10], st0[11]); w.z = cvtpk2(st0[12], st0[13]); w.w = cvtpk2(st0[14], st0[15]); pf[1] = __builtin_bit_cast(bf16x8, w);
;     w.x = cvtpk2(st1[0], st1[1]); w.y = cvtpk2(st1[2], st1[3]); w.z = cvtpk2(st1[4], st1[5]); w.w = cvtpk2(st1[6], st1[7]); pf[2] = __builtin_bit_cast(bf16x8, w);
;     w.x = cvtpk2(st1[8], st1[9]); w.y = cvtpk2(st1[10], st1[11]); w.z = cvtpk2(st1[12], st1[13]); w.w = cvtpk2(st1[14], st1[15]); pf[3] = __builtin_bit_cast(bf16x8, w);
; }
; __device__ __forceinline__ void a2_pv(const LAS unsigned char* vb, const bf16x8 (&pf)[4], f32x16& ot0, f32x16& ot1) {
; #pragma unroll
;     for (int s = 0; s < 4; ++s) {
;         const s16x4 a00 = __builtin_bit_cast(s16x4, __builtin_amdgcn_ds_read_tr16_b64_v4i16((LAS s16x4*)(vb + (16 * s) * 64)));
;         const s16x4 a01 = __builtin_bit_cast(s16x4, __builtin_amdgcn_ds_read_tr16_b64_v4i16((LAS s16x4*)(vb + (16 * s + 8) * 64)));
;         const s16x4 a10 = __builtin_bit_cast(s16x4, __builtin_amdgcn_ds_read_tr16_b64_v4i16((LAS s16x4*)(vb + 8192 + (16 * s) * 64)));
;         const s16x4 a11 = __builtin_bit_cast(s16x4, __builtin_amdgcn_ds_read_tr16_b64_v4i16((LAS s16x4*)(vb + 8192 + (16 * s + 8) * 64)));
;         const bf16x8 va0 = (bf16x8){a00[0], a00[1], a00[2], a00[3], a01[0], a01[1], a01[2], a01[3]};
;         const bf16x8 va1 = (bf16x8){a10[0], a10[1], a10[2], a10[3], a11[0], a11[1], a11[2], a11[3]};
; __device__ __forceinline__ void attn2_unit(bf16_t* Z, const bf16_t* Hb, const float* rc, const float* rs, LAS unsigned char* lds, int b, int h, int qblk) {
;     ...
;             a2_exp_pack(sa0, sa1, lsum, pa);
;             a2_pv(vb, pa, ot0, ot1);
;             a2_exp_pack(sb0, sb1, lsum, pb);
;             a2_pv(vb + 64 * 64, pb, ot0, ot1);
.LBB0_2289:
	v_add_u32_e32 v0, v2, v218
	v_exp_f32_e32 v195, v112
	v_exp_f32_e32 v7, v96
	v_exp_f32_e32 v113, v113
	v_exp_f32_e32 v9, v97
	v_exp_f32_e32 v199, v114
	v_exp_f32_e32 v3, v98
	v_exp_f32_e32 v115, v115
	v_exp_f32_e32 v5, v99
	v_exp_f32_e32 v201, v116
	v_exp_f32_e32 v15, v117
	v_exp_f32_e32 v13, v118
	v_exp_f32_e32 v11, v119
	s_waitcnt vmcnt(0)
	ds_read_b64_tr_b16 v[96:97], v0 offset:26624
	ds_read_b64_tr_b16 v[98:99], v0 offset:27136
	ds_read_b64_tr_b16 v[212:213], v0 offset:34816
	ds_read_b64_tr_b16 v[214:215], v0 offset:35328
	ds_read_b64_tr_b16 v[220:221], v0 offset:27648
	ds_read_b64_tr_b16 v[222:223], v0 offset:28160
	v_cvt_pk_bf16_f32 v208, v195, v113
	v_cvt_pk_bf16_f32 v209, v199, v115
	v_cvt_pk_bf16_f32 v210, v201, v15
	v_cvt_pk_bf16_f32 v211, v13, v11
	v_exp_f32_e32 v207, v120
	v_exp_f32_e32 v205, v121
	s_waitcnt lgkmcnt(4)
	v_mfma_f32_32x32x16_bf16 v[16:31], v[96:99], v[208:211], v[16:31]
	v_exp_f32_e32 v203, v122
	v_exp_f32_e32 v121, v123
	v_exp_f32_e32 v117, v124
	ds_read_b64_tr_b16 v[224:225], v0 offset:35840
	ds_read_b64_tr_b16 v[226:227], v0 offset:36352
	v_exp_f32_e32 v119, v125
	v_exp_f32_e32 v99, v126
	v_exp_f32_e32 v97, v127
	s_waitcnt lgkmcnt(4)
	v_mfma_f32_32x32x16_bf16 v[32:47], v[212:215], v[208:211], v[32:47]
	v_cvt_pk_bf16_f32 v228, v207, v205
	v_cvt_pk_bf16_f32 v229, v203, v121
	v_cvt_pk_bf16_f32 v230, v117, v119
	v_cvt_pk_bf16_f32 v231, v99, v97
	v_exp_f32_e32 v125, v100
	v_exp_f32_e32 v211, v101
	v_exp_f32_e32 v209, v102
	s_waitcnt lgkmcnt(2)
	v_mfma_f32_32x32x16_bf16 v[16:31], v[220:223], v[228:231], v[16:31]
	v_exp_f32_e32 v215, v103
	ds_read_b64_tr_b16 v[220:221], v0 offset:28672
	ds_read_b64_tr_b16 v[222:223], v0 offset:29184
	v_cvt_pk_bf16_f32 v100, v7, v9
	v_cvt_pk_bf16_f32 v101, v3, v5
	v_cvt_pk_bf16_f32 v102, v125, v211
	v_cvt_pk_bf16_f32 v103, v209, v215
	v_exp_f32_e32 v123, v104
	s_waitcnt lgkmcnt(2)
	v_mfma_f32_32x32x16_bf16 v[32:47], v[224:227], v[228:231], v[32:47]
	ds_read_b64_tr_b16 v[224:225], v0 offset:36864
	ds_read_b64_tr_b16 v[226:227], v0 offset:37376
	ds_read_b64_tr_b16 v[228:229], v0 offset:29696
	ds_read_b64_tr_b16 v[230:231], v0 offset:30208
	v_exp_f32_e32 v127, v105
	v_exp_f32_e32 v105, v106
	v_exp_f32_e32 v213, v107
	v_exp_f32_e32 v107, v108
	v_exp_f32_e32 v109, v109
	v_exp_f32_e32 v194, v64
	s_waitcnt lgkmcnt(4)
	v_mfma_f32_32x32x16_bf16 v[16:31], v[220:223], v[100:103], v[16:31]
	ds_read_b64_tr_b16 v[220:221], v0 offset:37888
	ds_read_b64_tr_b16 v[222:223], v0 offset:38400
	v_exp_f32_e32 v6, v80
	v_exp_f32_e32 v112, v65
	v_exp_f32_e32 v8, v81
	v_exp_f32_e32 v198, v66
	v_exp_f32_e32 v2, v82
	v_exp_f32_e32 v114, v67
	s_waitcnt lgkmcnt(4)
	v_mfma_f32_32x32x16_bf16 v[32:47], v[224:227], v[100:103], v[32:47]
	v_exp_f32_e32 v103, v110
	v_exp_f32_e32 v101, v111
	v_exp_f32_e32 v4, v83
	v_cvt_pk_bf16_f32 v224, v123, v127
	v_cvt_pk_bf16_f32 v225, v105, v213
	v_cvt_pk_bf16_f32 v226, v107, v109
	v_cvt_pk_bf16_f32 v227, v103, v101
	v_pk_add_f32 v[64:65], v[6:7], v[194:195]
	v_pk_add_f32 v[66:67], v[8:9], v[112:113]
	s_waitcnt lgkmcnt(2)
	v_mfma_f32_32x32x16_bf16 v[16:31], v[228:231], v[224:227], v[16:31]
	v_pk_add_f32 v[64:65], v[64:65], 0 op_sel_hi:[1,0]
	v_exp_f32_e32 v200, v68
	v_pk_add_f32 v[64:65], v[66:67], v[64:65]
	v_pk_add_f32 v[66:67], v[2:3], v[198:199]
	v_exp_f32_e32 v14, v69
	v_pk_add_f32 v[64:65], v[66:67], v[64:65]
	v_pk_add_f32 v[66:67], v[4:5], v[114:115]
	s_waitcnt lgkmcnt(0)
	v_mfma_f32_32x32x16_bf16 v[32:47], v[220:223], v[224:227], v[32:47]
	v_pk_add_f32 v[110:111], v[66:67], v[64:65]
	v_exp_f32_e32 v12, v70
	v_exp_f32_e32 v10, v71
	ds_read_b64_tr_b16 v[64:65], v0 offset:30720
	ds_read_b64_tr_b16 v[66:67], v0 offset:31232
	v_exp_f32_e32 v124, v84
	v_exp_f32_e32 v206, v72
	v_exp_f32_e32 v204, v73
	v_exp_f32_e32 v202, v74
	v_exp_f32_e32 v120, v75
	ds_read_b64_tr_b16 v[72:73], v0 offset:38912
	ds_read_b64_tr_b16 v[74:75], v0 offset:39424
	ds_read_b64_tr_b16 v[80:81], v0 offset:31744
	ds_read_b64_tr_b16 v[82:83], v0 offset:32256
	v_exp_f32_e32 v210, v85
	v_cvt_pk_bf16_f32 v68, v194, v112
	v_cvt_pk_bf16_f32 v69, v198, v114
	v_cvt_pk_bf16_f32 v70, v200, v14
	v_cvt_pk_bf16_f32 v71, v12, v10
	v_pk_add_f32 v[216:217], v[124:125], v[200:201]
	v_exp_f32_e32 v208, v86
	s_waitcnt lgkmcnt(4)
; __device__ __forceinline__ void attn2_unit(bf16_t* Z, const bf16_t* Hb, const float* rc, const float* rs, LAS unsigned char* lds, int b, int h, int qblk) {
;     ...
;             a2_exp_pack(sa0, sa1, lsum, pa);
;             a2_pv(vb, pa, ot0, ot1);
;             a2_exp_pack(sb0, sb1, lsum, pb);
;             a2_pv(vb + 64 * 64, pb, ot0, ot1);
;         } else if (2 * kp <= cw) {
;             f32x16 sa0, sa1; bf16x8 pa[4];
;             a2_qk(kb, qf, cneg, sa0, sa1);
;             const float mt = a2_max(sa0, sa1);
;             if (kp == 0 || __builtin_amdgcn_ballot_w64(mt > 8.f) != 0ull) {
;                 const float delta = (kp == 0) ? mt : fmaxf(mt, 0.f), alpha = (kp == 0) ? 0.f : __builtin_amdgcn_exp2f(-delta);
;                 mrun += delta; lsum *= alpha;
; #pragma unroll
;                 for (int r = 0; r < 16; ++r) { ot0[r] *= alpha; ot1[r] *= alpha; sa0[r] -= delta; sa1[r] -= delta; cneg[r] = -mrun; }
;             }
;             a2_exp_pack(sa0, sa1, lsum, pa);
;             a2_pv(vb, pa, ot0, ot1);
;         }
;         __syncthreads();
;     }
	v_mfma_f32_32x32x16_bf16 v[16:31], v[64:67], v[68:71], v[16:31]
	v_pk_add_f32 v[64:65], v[216:217], v[110:111]
	v_pk_add_f32 v[14:15], v[210:211], v[14:15]
	v_exp_f32_e32 v214, v87
	v_exp_f32_e32 v116, v76
	v_exp_f32_e32 v118, v77
	v_exp_f32_e32 v98, v78
	v_exp_f32_e32 v96, v79
	s_waitcnt lgkmcnt(2)
	v_mfma_f32_32x32x16_bf16 v[32:47], v[72:75], v[68:71], v[32:47]
	v_pk_add_f32 v[14:15], v[14:15], v[64:65]
	ds_read_b64_tr_b16 v[64:65], v0 offset:39936
	ds_read_b64_tr_b16 v[66:67], v0 offset:40448
	v_exp_f32_e32 v122, v88
	v_pk_add_f32 v[12:13], v[208:209], v[12:13]
	v_pk_add_f32 v[68:69], v[214:215], v[10:11]
	v_pk_add_f32 v[14:15], v[12:13], v[14:15]
	v_cvt_pk_bf16_f32 v10, v206, v204
	v_cvt_pk_bf16_f32 v11, v202, v120
	v_cvt_pk_bf16_f32 v12, v116, v118
	v_cvt_pk_bf16_f32 v13, v98, v96
	v_pk_add_f32 v[14:15], v[68:69], v[14:15]
	v_pk_add_f32 v[68:69], v[122:123], v[206:207]
	s_waitcnt lgkmcnt(2)
	v_mfma_f32_32x32x16_bf16 v[16:31], v[80:83], v[10:13], v[16:31]
	v_pk_add_f32 v[14:15], v[68:69], v[14:15]
	ds_read_b64_tr_b16 v[68:69], v0 offset:32768
	ds_read_b64_tr_b16 v[70:71], v0 offset:33280
	v_exp_f32_e32 v126, v89
	v_exp_f32_e32 v104, v90
	v_cvt_pk_bf16_f32 v7, v2, v4
	v_exp_f32_e32 v212, v91
	v_cvt_pk_bf16_f32 v6, v6, v8
	s_waitcnt lgkmcnt(2)
	v_mfma_f32_32x32x16_bf16 v[32:47], v[64:67], v[10:13], v[32:47]
	ds_read_b64_tr_b16 v[2:3], v0 offset:40960
	ds_read_b64_tr_b16 v[4:5], v0 offset:41472
	ds_read_b64_tr_b16 v[10:11], v0 offset:33792
	ds_read_b64_tr_b16 v[12:13], v0 offset:34304
	v_cvt_pk_bf16_f32 v8, v124, v210
	v_cvt_pk_bf16_f32 v9, v208, v214
	v_pk_add_f32 v[72:73], v[126:127], v[204:205]
	v_pk_add_f32 v[64:65], v[104:105], v[202:203]
	v_pk_add_f32 v[14:15], v[72:73], v[14:15]
	v_exp_f32_e32 v106, v92
	s_waitcnt lgkmcnt(4)
	v_mfma_f32_32x32x16_bf16 v[16:31], v[68:71], v[6:9], v[16:31]
	v_pk_add_f32 v[14:15], v[64:65], v[14:15]
	v_pk_add_f32 v[64:65], v[212:213], v[120:121]
	v_exp_f32_e32 v108, v93
	v_exp_f32_e32 v102, v94
	v_exp_f32_e32 v100, v95
	v_pk_add_f32 v[14:15], v[64:65], v[14:15]
	ds_read_b64_tr_b16 v[64:65], v0 offset:41984
	ds_read_b64_tr_b16 v[66:67], v0 offset:42496
	s_waitcnt lgkmcnt(4)
	v_mfma_f32_32x32x16_bf16 v[32:47], v[2:5], v[6:9], v[32:47]
	v_pk_add_f32 v[2:3], v[106:107], v[116:117]
	v_cvt_pk_bf16_f32 v4, v106, v108
	v_pk_add_f32 v[6:7], v[2:3], v[14:15]
	v_cvt_pk_bf16_f32 v2, v122, v126
	v_cvt_pk_bf16_f32 v3, v104, v212
	v_cvt_pk_bf16_f32 v5, v102, v100
	v_pk_add_f32 v[8:9], v[108:109], v[118:119]
	v_mov_b32_e32 v14, v55
	s_waitcnt lgkmcnt(2)
	v_mfma_f32_32x32x16_bf16 v[16:31], v[10:13], v[2:5], v[16:31]
	v_pk_add_f32 v[6:7], v[8:9], v[6:7]
	v_pk_add_f32 v[8:9], v[102:103], v[98:99]
	v_mov_b32_e32 v10, v59
	v_pk_add_f32 v[6:7], v[8:9], v[6:7]
	v_pk_add_f32 v[8:9], v[100:101], v[96:97]
	v_mov_b32_e32 v11, v58
	v_pk_add_f32 v[6:7], v[8:9], v[6:7]
	s_waitcnt lgkmcnt(0)
	v_mfma_f32_32x32x16_bf16 v[32:47], v[64:67], v[2:5], v[32:47]
	v_add_f32_e32 v0, v169, v7
	v_add_f32_e32 v0, v6, v0
	s_add_i32 s31, s31, 1
	s_add_i32 s42, s42, 2
	s_add_i32 s6, s38, s31
	v_lshl_add_u64 v[174:175], v[174:175], 0, v[170:171]
	v_lshl_add_u64 v[176:177], v[176:177], 0, s[18:19]
	v_lshl_add_u64 v[178:179], v[178:179], 0, s[18:19]
	v_lshl_add_u64 v[182:183], v[182:183], 0, v[180:181]
	v_lshl_add_u64 v[186:187], v[186:187], 0, v[184:185]
	s_cmp_lg_u32 s6, 1
	v_lshl_add_u64 v[190:191], v[190:191], 0, v[188:189]
	s_waitcnt vmcnt(0) lgkmcnt(0)
	s_barrier
	s_cbranch_scc0 .Lattn_exit_3
	v_mov_b32_e32 v169, v0
	s_bitcmp1_b32 s31, 0
	s_cselect_b32 s6, 0, 0xa800
	s_cmp_ge_u32 s31, s36
	s_cbranch_scc0 .LBB0_2267
	s_branch .LBB0_2270
